# v48 + hgrn_r3 chunk-top: norm-sum ds_read_b128 pairs 2 and 3 prefetched together with pair 1 into v214-229 (counted lgkmcnt 5/4/2/0), consumers read the prefetch registers directly
# baseline (speedup 1.0000x reference)
; #define LAS __attribute__((address_space(3)))
; #define GAS __attribute__((address_space(1)))
; __device__ __forceinline__ unsigned pkbf(float lo, float hi) { const f32x2_t v = {lo, hi}; const bf16x2_t b = __builtin_convertvector(v, bf16x2_t); return __builtin_bit_cast(unsigned, b); }
; __device__ __forceinline__ float lo16(unsigned w) { return __uint_as_float(w << 16); }
; __device__ __forceinline__ float hi16(unsigned w) { return __uint_as_float(w & 0xffff0000u); }
; __device__ __forceinline__ void hgrn_r3(const GAS bf16* proj, const GAS float* RU, const GAS float* RD, GAS bf16* y, int TOKG, const GAS float* ogain, unsigned char* lds, int tid, int lane, int wave, int bid, int G) {
;     ...
;             __syncthreads();
; #pragma unroll
;             for (int t2 = 0; t2 < 4; ++t2) { const int t = 16 * t2 + fr; float tot = 0.f;
; #pragma unroll
;                 for (int w8 = 0; w8 < 2; ++w8) { const f32x4h pr = *(const LAS f32x4h*)(red + t * 8 + 4 * w8); tot += (pr[0] + pr[1]) + (pr[2] + pr[3]); }
;                 const float rstd = rsqrtf(tot * (1.f / 128.f) + EPS);
;                 v2u w; w.x = pkbf(acc[t2][0] * rstd * og.x * lo16(zw[t2].x), acc[t2][1] * rstd * og.y * hi16(zw[t2].x));
;                 w.y = pkbf(acc[t2][2] * rstd * og.z * lo16(zw[t2].y), acc[t2][3] * rstd * og.w * hi16(zw[t2].y));
;                 *(GAS v2u*)((GAS char*)(y + rowc * MW + h * 128) + yoff[t2]) = w; }
.LBB0_383:
	s_or_b64 exec, exec, vcc
	s_waitcnt lgkmcnt(0)
	s_barrier
	ds_read_b128 v[40:43], v133
	ds_read_b128 v[44:47], v133 offset:16
	s_mov_b32 s64, 0x358637bd
	s_add_i32 s80, s80, 1
	s_lshl_b64 s[42:43], s[42:43], 12
	s_waitcnt lgkmcnt(1)
	v_mov_b32_e32 v56, v40
	s_waitcnt lgkmcnt(0)
	v_mov_b32_e32 v57, v44
	v_mov_b32_e32 v44, v41
	v_mov_b32_e32 v40, v42
	v_mov_b32_e32 v41, v46
	v_mov_b32_e32 v46, v43
	v_pk_add_f32 v[56:57], v[56:57], v[44:45]
	v_pk_add_f32 v[58:59], v[40:41], v[46:47]
	ds_read_b128 v[40:43], v133 offset:512
	ds_read_b128 v[44:47], v133 offset:528
	ds_read_b128 v[214:217], v133 offset:1024
	ds_read_b128 v[218:221], v133 offset:1040
	ds_read_b128 v[222:225], v133 offset:1536
	ds_read_b128 v[226:229], v133 offset:1552
	v_pk_add_f32 v[56:57], v[56:57], v[58:59]
	s_waitcnt vmcnt(3)
	v_lshlrev_b32_e32 v58, 16, v96
	v_and_b32_e32 v59, 0xffff0000, v96
	s_waitcnt lgkmcnt(5)
	v_mov_b32_e32 v60, v40
	s_waitcnt lgkmcnt(4)
	v_mov_b32_e32 v61, v44
	v_mov_b32_e32 v44, v41
	v_pk_add_f32 v[40:41], v[60:61], v[44:45]
	v_mov_b32_e32 v44, v42
	v_mov_b32_e32 v45, v46
	v_mov_b32_e32 v46, v43
	v_pk_add_f32 v[42:43], v[44:45], v[46:47]
	s_add_u32 s42, s78, s42
	v_pk_add_f32 v[40:41], v[40:41], v[42:43]
	v_mov_b32_e32 v43, v56
	v_mov_b32_e32 v42, v40
	v_pk_add_f32 v[42:43], v[42:43], 0 op_sel_hi:[1,0]
	v_mov_b32_e32 v56, v41
	v_pk_add_f32 v[40:41], v[42:43], v[56:57]
	v_mov_b64_e32 v[56:57], s[64:65]
	v_pk_fma_f32 v[40:41], v[40:41], s[90:91], v[56:57] op_sel_hi:[1,0,0]
	v_and_b32_e32 v43, 0xffff0000, v97
	v_mul_f32_e32 v42, 0x4b800000, v41
	v_cmp_gt_f32_e32 vcc, s92, v41
	s_addc_u32 s43, s79, s43
	v_lshl_add_u64 v[44:45], s[42:43], 0, v[80:81]
	v_cndmask_b32_e32 v41, v41, v42, vcc
	v_rsq_f32_e32 v41, v41
	v_lshlrev_b32_e32 v42, 16, v97
	s_add_i32 s69, s69, 0x8000
	s_add_i32 s77, s77, 0x80000
	v_mul_f32_e32 v46, 0x45800000, v41
	v_cndmask_b32_e32 v46, v41, v46, vcc
	v_pk_mul_f32 v[60:61], v[64:65], v[46:47] op_sel_hi:[1,0]
	v_mul_f32_e32 v41, 0x4b800000, v40
	v_cmp_gt_f32_e32 vcc, s92, v40
	v_pk_mul_f32 v[60:61], v[0:1], v[60:61]
	v_pk_mul_f32 v[46:47], v[66:67], v[46:47] op_sel_hi:[1,0]
	v_cndmask_b32_e32 v40, v40, v41, vcc
	v_pk_mul_f32 v[58:59], v[60:61], v[58:59]
	v_rsq_f32_e32 v60, v40
	v_pk_mul_f32 v[46:47], v[2:3], v[46:47]
	v_cvt_pk_bf16_f32 v58, v58, v59
	v_pk_mul_f32 v[40:41], v[46:47], v[42:43]
	s_add_i32 s81, s81, 64
	v_cvt_pk_bf16_f32 v59, v40, v41
	v_mul_f32_e32 v40, 0x45800000, v60
	v_cndmask_b32_e32 v40, v60, v40, vcc
	v_pk_mul_f32 v[42:43], v[52:53], v[40:41] op_sel_hi:[1,0]
	global_store_dwordx2 v[44:45], v[58:59], off
	v_pk_mul_f32 v[42:43], v[0:1], v[42:43]
	s_waitcnt vmcnt(3)
	v_lshlrev_b32_e32 v44, 16, v94
	v_and_b32_e32 v45, 0xffff0000, v94
	v_pk_mul_f32 v[42:43], v[42:43], v[44:45]
	v_pk_mul_f32 v[40:41], v[54:55], v[40:41] op_sel_hi:[1,0]
	v_cvt_pk_bf16_f32 v52, v42, v43
	v_pk_mul_f32 v[40:41], v[2:3], v[40:41]
	v_lshlrev_b32_e32 v42, 16, v95
	v_and_b32_e32 v43, 0xffff0000, v95
	v_pk_mul_f32 v[54:55], v[40:41], v[42:43]
	v_cvt_pk_bf16_f32 v53, v54, v55
	v_lshl_add_u64 v[54:55], s[42:43], 0, v[76:77]
	global_store_dwordx2 v[54:55], v[52:53], off
	s_waitcnt lgkmcnt(2)
	v_mov_b32_e32 v52, v214
	v_mov_b32_e32 v53, v218
	v_mov_b32_e32 v44, v215
	v_mov_b32_e32 v45, v219
	v_mov_b32_e32 v40, v216
	v_mov_b32_e32 v41, v220
	v_mov_b32_e32 v46, v217
	v_mov_b32_e32 v47, v221
	v_pk_add_f32 v[52:53], v[52:53], v[44:45]
	v_pk_add_f32 v[54:55], v[40:41], v[46:47]
	v_pk_add_f32 v[52:53], v[52:53], v[54:55]
	s_waitcnt vmcnt(3)
	v_lshlrev_b32_e32 v54, 16, v92
	v_and_b32_e32 v55, 0xffff0000, v92
	s_waitcnt lgkmcnt(0)
	v_mov_b32_e32 v58, v222
	v_mov_b32_e32 v59, v226
	v_mov_b32_e32 v44, v223
	v_mov_b32_e32 v45, v227
	v_pk_add_f32 v[40:41], v[58:59], v[44:45]
	v_mov_b32_e32 v44, v224
	v_mov_b32_e32 v45, v228
	v_mov_b32_e32 v46, v225
	v_mov_b32_e32 v47, v229
	v_pk_add_f32 v[42:43], v[44:45], v[46:47]
	v_lshl_add_u64 v[44:45], s[42:43], 0, v[72:73]
	v_pk_add_f32 v[40:41], v[40:41], v[42:43]
	v_mov_b32_e32 v43, v52
	v_mov_b32_e32 v42, v40
	v_pk_add_f32 v[42:43], v[42:43], 0 op_sel_hi:[1,0]
	v_mov_b32_e32 v52, v41
	v_pk_add_f32 v[40:41], v[42:43], v[52:53]
	v_and_b32_e32 v43, 0xffff0000, v93
	v_pk_fma_f32 v[40:41], v[40:41], s[90:91], v[56:57] op_sel_hi:[1,0,0]
	s_cmp_eq_u32 s80, 16
	v_mul_f32_e32 v42, 0x4b800000, v41
	v_cmp_gt_f32_e32 vcc, s92, v41
	v_mov_b32_e32 v62, v112
	v_mov_b32_e32 v63, v114
	v_cndmask_b32_e32 v41, v41, v42, vcc
	v_rsq_f32_e32 v41, v41
	v_lshlrev_b32_e32 v42, 16, v93
	v_mov_b32_e32 v64, v136
	v_mov_b32_e32 v65, v138
	v_mul_f32_e32 v46, 0x45800000, v41
	v_cndmask_b32_e32 v46, v41, v46, vcc
	v_mul_f32_e32 v41, 0x4b800000, v40
	v_cmp_gt_f32_e32 vcc, s92, v40
	v_pk_mul_f32 v[48:49], v[48:49], v[46:47] op_sel_hi:[1,0]
	v_pk_mul_f32 v[46:47], v[50:51], v[46:47] op_sel_hi:[1,0]
	v_cndmask_b32_e32 v40, v40, v41, vcc
	v_rsq_f32_e32 v50, v40
	v_pk_mul_f32 v[48:49], v[0:1], v[48:49]
	v_pk_mul_f32 v[46:47], v[2:3], v[46:47]
	v_pk_mul_f32 v[48:49], v[48:49], v[54:55]
	v_pk_mul_f32 v[40:41], v[46:47], v[42:43]
	v_cvt_pk_bf16_f32 v48, v48, v49
	v_cvt_pk_bf16_f32 v49, v40, v41
	v_mul_f32_e32 v40, 0x45800000, v50
	v_cndmask_b32_e32 v40, v50, v40, vcc
	v_pk_mul_f32 v[36:37], v[36:37], v[40:41] op_sel_hi:[1,0]
	v_pk_mul_f32 v[38:39], v[38:39], v[40:41] op_sel_hi:[1,0]
	v_pk_mul_f32 v[36:37], v[0:1], v[36:37]
	s_waitcnt vmcnt(2)
	v_lshlrev_b32_e32 v42, 16, v90
	v_and_b32_e32 v43, 0xffff0000, v90
	v_pk_mul_f32 v[38:39], v[2:3], v[38:39]
	v_lshlrev_b32_e32 v40, 16, v91
	v_and_b32_e32 v41, 0xffff0000, v91
	v_pk_mul_f32 v[36:37], v[36:37], v[42:43]
	v_pk_mul_f32 v[38:39], v[38:39], v[40:41]
	v_cvt_pk_bf16_f32 v36, v36, v37
	v_cvt_pk_bf16_f32 v37, v38, v39
	v_lshl_add_u64 v[38:39], s[42:43], 0, v[68:69]
	v_mov_b32_e32 v66, v141
	v_mov_b32_e32 v67, v144
	v_mov_b32_e32 v157, v147
	v_mov_b32_e32 v158, v150
	v_mov_b32_e32 v163, v115
	v_mov_b32_e32 v161, v137
	v_mov_b32_e32 v61, v140
	v_mov_b32_e32 v59, v143
	v_mov_b32_e32 v57, v146
	v_mov_b32_e32 v55, v149
	v_mov_b32_e32 v52, v152
	v_mov_b32_e32 v54, v154
	v_mov_b32_e32 v164, v139
	v_mov_b32_e32 v162, v142
	v_mov_b32_e32 v160, v145
	v_mov_b32_e32 v60, v148
	v_mov_b32_e32 v58, v151
	v_mov_b32_e32 v56, v153
	v_mov_b32_e32 v53, v155
	v_mov_b32_e32 v159, v156
	global_store_dwordx2 v[44:45], v[48:49], off
	global_store_dwordx2 v[38:39], v[36:37], off
	s_cbranch_scc1 .LBB0_377
